# MLA SwiGLU: compiler's pre-loop vmcnt(0) (preheader flush) removed; the peeled iteration's counted waits cover the reads
# speedup vs baseline: 1.0039x; 1.0039x over previous
.LBB0_1143:
	s_add_u32 s28, s28, 0x80
	s_addc_u32 s29, s29, 0
	s_add_u32 s10, s30, 0x100
	s_addc_u32 s11, s31, 0
	s_mov_b32 s16, 0
	s_cmp_lg_u32 s100, 0
	s_cbranch_scc0 .Llbb_10
	s_barrier
	s_mov_b32 s100, 0
